# grid barrier: XCD leader bumps the per-XCD generation before its own L1 invalidate (other workgroups released earlier), on top of v6
# speedup vs baseline: 1.0069x; 1.0069x over previous
; __device__ __forceinline__ unsigned xb_ld(unsigned* p)              { return __hip_atomic_load(p, __ATOMIC_RELAXED, __HIP_MEMORY_SCOPE_AGENT); }
; __device__ __forceinline__ unsigned xb_add(unsigned* p, unsigned v) { return __hip_atomic_fetch_add(p, v, __ATOMIC_RELAXED, __HIP_MEMORY_SCOPE_AGENT); }
; #define XB_SPIN(cond, bar) do { unsigned _sp = 0; while (cond) { __builtin_amdgcn_s_sleep(1); \
;     if ((++_sp & 255u) == 0u) { if (xb_ld(&(bar)[XB_TMO])) break; if (_sp > XB_SPIN_CAP) { atomicAdd(&(bar)[XB_TMO], 1u); break; } } } } while (0)
; __device__ __forceinline__ void xcd_barrier(const XcdBarrier& b) {
;     ...
;             else XB_SPIN(xb_ld(&bar[XB_TOPGEN]) == tg, bar);
;             __builtin_amdgcn_fence(__ATOMIC_ACQUIRE, "agent");
;             xb_add(&bar[XB_XGEN(b.x)], 1u);
;             asm volatile("s_waitcnt vmcnt(0)" ::: "memory");
.LBB0_225:
	s_or_b64 exec, exec, s[4:5]
	s_mov_b64 s[4:5], exec
	v_mbcnt_lo_u32_b32 v0, s4, 0
	v_mbcnt_hi_u32_b32 v0, s5, v0
	v_cmp_eq_u32_e32 vcc, 0, v0
	s_waitcnt vmcnt(0)
	s_and_saveexec_b64 s[6:7], vcc
	s_cbranch_execz .LBB0_227
	s_bcnt1_i32_b64 s4, s[4:5]
	v_mov_b32_e32 v0, 0x2000
	v_mov_b32_e32 v1, s4
	global_atomic_add v0, v1, s[2:3] offset:1024
.LBB0_227:
	s_or_b64 exec, exec, s[6:7]
	buffer_inv sc1
	s_waitcnt vmcnt(0)
